# in-proj: per-row sum-of-squares loads hoisted to the unit header (same as FFN-up)
# baseline (speedup 1.0000x reference)
; __device__ __forceinline__ bool unit_at(const GemmD& g, int G, int c, int i, int& pm, int& pn, int& z) {
;     const int L = i * G + c; const int per = g.nM * g.nN; if (L >= per * g.nZ) return false;
;     z = L / per; int wgid = L % per;
;     { const int q = per / NXCD, r = per % NXCD, xcd = wgid % NXCD, off = wgid / NXCD; wgid = (xcd < r ? xcd * (q + 1) : r * (q + 1) + (xcd - r) * q) + off; }
;     const int nig = WGM * g.nN, gid = wgid / nig, fm = gid * WGM, gsz = (g.nM - fm) < WGM ? (g.nM - fm) : WGM;
;     pm = fm + ((wgid % nig) % gsz); pn = (wgid % nig) / gsz; return true;
;     __device__ __forceinline__ void operator()(AccRef acc, int pm, int pn, int z, int wr, int wc, int fr, int fq) const {
;     ...
;             for (int m = 0; m < 4; ++m) rrow[ai][m] = rsq[row0 + ai * HALF + m * 16];
.LBB0_391:
	v_lshl_add_u32 v250, s2, 8, v153
	v_ashrrev_i32_e32 v251, 31, v250
	v_lshl_add_u64 v[250:251], v[250:251], 2, s[12:13]
	global_load_dword v241, v[250:251], off
	global_load_dword v242, v[250:251], off offset:64
	global_load_dword v243, v[250:251], off offset:128
	global_load_dword v244, v[250:251], off offset:192
	global_load_dword v245, v[250:251], off offset:512
	global_load_dword v246, v[250:251], off offset:576
	global_load_dword v247, v[250:251], off offset:640
	global_load_dword v248, v[250:251], off offset:704
	s_add_i32 s83, s83, 1
	v_readlane_b32 s4, v240, 0
	s_mul_i32 s4, s83, s4
	s_add_i32 s4, s4, s53
	s_cmpk_lt_i32 s4, 0xa00
	s_cselect_b64 s[64:65], -1, 0
	s_cmpk_gt_i32 s4, 0x9ff
	v_readlane_b32 s5, v240, 1
	s_cbranch_scc1 .LBB0_393
	s_mul_hi_i32 s5, s4, 0x66666667
	s_lshr_b32 s6, s5, 31
	s_ashr_i32 s5, s5, 10
	s_add_i32 s5, s5, s6
	s_mulk_i32 s5, 0xa00
	s_sub_i32 s4, s4, s5
	s_sext_i32_i16 s5, s4
	s_bfe_u32 s5, s5, 0x3001c
	s_add_i32 s5, s4, s5
	s_sext_i32_i16 s6, s5
	s_and_b32 s5, s5, 0xfff8
	s_sub_i32 s4, s4, s5
	s_ashr_i32 s6, s6, 3
	s_sext_i32_i16 s5, s4
	s_cmp_lt_i32 s5, 0
	s_movk_i32 s5, 0x141
	s_cselect_b32 s5, s5, 0x140
	s_mul_i32 s4, s4, s5
	s_add_i32 s4, s4, s6
	s_sext_i32_i16 s5, s4
	s_mulk_i32 s5, 0x6667
	s_lshr_b32 s6, s5, 31
	s_ashr_i32 s5, s5, 22
	s_add_i32 s5, s5, s6
	s_lshl_b32 s6, s5, 2
	s_mulk_i32 s5, 0xa0
	s_sub_i32 s4, s4, s5
	s_sext_i32_i16 s5, s4
	s_bfe_u32 s5, s5, 0x2001d
	s_add_i32 s5, s4, s5
	s_sext_i32_i16 s10, s5
	s_and_b32 s5, s5, 0xfffc
	s_sub_i32 s4, s4, s5
	s_sext_i32_i16 s4, s4
	s_add_i32 s60, s6, s4
	s_ashr_i32 s62, s10, 2

; #define PG8_STAGE(bufoff, gbase, voff) do { _Pragma("unroll") for (int _i = 0; _i < 2; ++_i) \
;         __builtin_amdgcn_global_load_lds((const unsigned*)((const char*)(gbase) + (voff)[_i]), (LAS unsigned*)(lds + (bufoff) + ldsw + _i * 8192), 16, 0, 0); } while (0)
; #define PG8_LDA(dst, b, h) do { _Pragma("unroll") for (int m = 0; m < 4; ++m) _Pragma("unroll") for (int k = 0; k < 2; ++k) dst[m][k] = *(const LAS bf16x8*)(lds + PG8_SA(b, h) + aoff + m * 2048 + k * 1024); } while (0)
; #define PG8_LDB(dst, b, h) do { _Pragma("unroll") for (int n = 0; n < 2; ++n) _Pragma("unroll") for (int k = 0; k < 2; ++k) dst[n][k] = *(const LAS bf16x8*)(lds + PG8_SB(b, h) + boff + n * 2048 + k * 1024); } while (0)
; #define PG8_MMA(ai, bj, At, Bt) do { __builtin_amdgcn_s_setprio(1); _Pragma("unroll") for (int m = 0; m < 4; ++m) _Pragma("unroll") for (int n = 0; n < 2; ++n) _Pragma("unroll") for (int k = 0; k < 2; ++k) \
;         acc[ai][bj][m][n] = __builtin_amdgcn_mfma_f32_16x16x32_bf16(Bt[n][k], At[m][k], acc[ai][bj][m][n], 0, 0, 0); __builtin_amdgcn_s_setprio(0); } while (0)
; #define PG8_WAIT_V(n) asm volatile("s_waitcnt vmcnt(" #n ")" ::: "memory")
; #define PG8_WAIT_L(n) asm volatile("s_waitcnt lgkmcnt(" #n ")" ::: "memory")
; #define PG8_BAR __builtin_amdgcn_s_barrier()
; #define PG8_SCHED __builtin_amdgcn_sched_barrier(0)
; template <class Epi>
; __device__ __forceinline__ void gemm_phase(LAS unsigned char* lds, const GemmD g, const Epi& E, int G, int c) {
;     ...
;         for (int t = 0; t < nt; t += 2) {
;             const bool last = (t == nt - 2);
;             const char* a1 = cA + (size_t)(t + 1) * kstep;
;             const char* a2 = last ? nA : cA + (size_t)(t + 2) * kstep; const char* b2 = last ? nB : cB + (size_t)(t + 2) * kstep;
;             const char* a3 = a2 + kstep; const char* b3 = b2 + kstep;
;             PG8_LDB(B0, 0, 0); PG8_LDB(B1, 0, 1); PG8_SCHED; PG8_LDA(At, 0, 0); PG8_STAGE(PG8_SA(1, 1), a1 + hstepA, voffA);
;             PG8_WAIT_V(8); PG8_WAIT_L(0); PG8_BAR; PG8_MMA(0, 0, At, B0); PG8_MMA(0, 1, At, B1); PG8_BAR; PG8_SCHED;
;             PG8_LDA(At, 0, 1); PG8_STAGE(PG8_SB(0, 0), b2, voffB); PG8_STAGE(PG8_SB(0, 1), b2 + hstepB, voffB); PG8_STAGE(PG8_SA(0, 0), a2, voffA);
;             PG8_WAIT_V(8); PG8_WAIT_L(0); PG8_BAR; PG8_MMA(1, 0, At, B0); PG8_MMA(1, 1, At, B1); PG8_BAR; PG8_SCHED;
.LBB0_394:
	s_add_u32 s4, s42, 0xfff80080
	s_addc_u32 s5, s43, -1
	s_add_i32 s28, 0, 0x10000
	s_cmp_eq_u32 s27, 28
	s_cselect_b32 s5, s6, s5
	s_cselect_b32 s4, s10, s4
	s_cselect_b32 s81, s11, s22
	s_cselect_b32 s80, s17, s19
	s_add_i32 s31, 0, 0x14000
	v_add_u32_e32 v140, s28, v194
	v_add_u32_e32 v174, s31, v194
	ds_read_b128 v[128:131], v140
	ds_read_b128 v[132:135], v140 offset:1024
	ds_read_b128 v[136:139], v140 offset:2048
	ds_read_b128 v[140:143], v140 offset:3072
	ds_read_b128 v[162:165], v174
	ds_read_b128 v[166:169], v174 offset:1024
	ds_read_b128 v[170:173], v174 offset:2048
	ds_read_b128 v[180:183], v174 offset:3072
	v_lshl_add_u64 v[174:175], s[42:43], 0, v[158:159]
	s_add_i32 m0, s23, 0xc000
	ds_read_b128 v[184:187], v196
	ds_read_b128 v[188:191], v196 offset:1024
	ds_read_b128 v[210:213], v196 offset:2048
	ds_read_b128 v[214:217], v196 offset:3072
	ds_read_b128 v[218:221], v196 offset:4096
	ds_read_b128 v[222:225], v196 offset:5120
	ds_read_b128 v[226:229], v196 offset:6144
	ds_read_b128 v[230:233], v196 offset:7168
	global_load_lds_dwordx4 v[174:175], off
	v_lshl_add_u64 v[174:175], s[42:43], 0, v[160:161]
	s_add_i32 m0, s23, 0xe000
	s_nop 0
	global_load_lds_dwordx4 v[174:175], off
	s_cmp_lg_u32 s99, 0
	s_cbranch_scc1 .Lrw_In_0_r
	s_waitcnt vmcnt(8)
	s_branch .Lrw_In_0_d
.Lrw_In_0_r:
	s_waitcnt vmcnt(24)
.Lrw_In_0_d:
	s_waitcnt lgkmcnt(0)
	s_barrier
	s_setprio 1
	s_waitcnt lgkmcnt(0)
	v_mfma_f32_16x16x32_bf16 v[124:127], v[128:131], v[184:187], v[124:127]
	v_mfma_f32_16x16x32_bf16 v[120:123], v[136:139], v[184:187], v[120:123]
	v_mfma_f32_16x16x32_bf16 v[108:111], v[128:131], v[210:213], v[108:111]
	v_mfma_f32_16x16x32_bf16 v[104:107], v[136:139], v[210:213], v[104:107]
	v_mfma_f32_16x16x32_bf16 v[92:95], v[128:131], v[218:221], v[92:95]
	v_mfma_f32_16x16x32_bf16 v[88:91], v[136:139], v[218:221], v[88:91]
	v_mfma_f32_16x16x32_bf16 v[76:79], v[128:131], v[226:229], v[76:79]
	v_mfma_f32_16x16x32_bf16 v[72:75], v[136:139], v[226:229], v[72:75]
	v_mfma_f32_16x16x32_bf16 v[124:127], v[132:135], v[188:191], v[124:127]
	v_mfma_f32_16x16x32_bf16 v[120:123], v[140:143], v[188:191], v[120:123]
	v_mfma_f32_16x16x32_bf16 v[108:111], v[132:135], v[214:217], v[108:111]
	v_mfma_f32_16x16x32_bf16 v[104:107], v[140:143], v[214:217], v[104:107]
	v_mfma_f32_16x16x32_bf16 v[92:95], v[132:135], v[222:225], v[92:95]
	v_mfma_f32_16x16x32_bf16 v[88:91], v[140:143], v[222:225], v[88:91]
	v_mfma_f32_16x16x32_bf16 v[76:79], v[132:135], v[230:233], v[76:79]
	v_mfma_f32_16x16x32_bf16 v[72:75], v[140:143], v[230:233], v[72:75]
	s_setprio 0
	s_setprio 1
	v_mfma_f32_16x16x32_bf16 v[116:119], v[162:165], v[184:187], v[116:119]
	v_mfma_f32_16x16x32_bf16 v[112:115], v[170:173], v[184:187], v[112:115]
	v_mfma_f32_16x16x32_bf16 v[100:103], v[162:165], v[210:213], v[100:103]
	v_mfma_f32_16x16x32_bf16 v[96:99], v[170:173], v[210:213], v[96:99]
	v_mfma_f32_16x16x32_bf16 v[84:87], v[162:165], v[218:221], v[84:87]
	v_mfma_f32_16x16x32_bf16 v[80:83], v[170:173], v[218:221], v[80:83]
	v_mfma_f32_16x16x32_bf16 v[68:71], v[162:165], v[226:229], v[68:71]
	v_mfma_f32_16x16x32_bf16 v[64:67], v[170:173], v[226:229], v[64:67]
	v_mfma_f32_16x16x32_bf16 v[116:119], v[166:169], v[188:191], v[116:119]
	v_mfma_f32_16x16x32_bf16 v[112:115], v[180:183], v[188:191], v[112:115]
	v_mfma_f32_16x16x32_bf16 v[100:103], v[166:169], v[214:217], v[100:103]
	v_mfma_f32_16x16x32_bf16 v[96:99], v[180:183], v[214:217], v[96:99]
	v_mfma_f32_16x16x32_bf16 v[84:87], v[166:169], v[222:225], v[84:87]
	v_mfma_f32_16x16x32_bf16 v[80:83], v[180:183], v[222:225], v[80:83]
	v_mfma_f32_16x16x32_bf16 v[68:71], v[166:169], v[230:233], v[68:71]
	v_mfma_f32_16x16x32_bf16 v[64:67], v[180:183], v[230:233], v[64:67]
	s_setprio 0
	s_barrier
	s_add_i32 s28, s28, s16
	v_lshl_add_u64 v[174:175], s[80:81], 0, v[148:149]
	s_mov_b32 m0, s28
	ds_read_b128 v[184:187], v196 offset:16384
	ds_read_b128 v[188:191], v196 offset:17408
	ds_read_b128 v[210:213], v196 offset:18432
	ds_read_b128 v[214:217], v196 offset:19456
	ds_read_b128 v[218:221], v196 offset:20480
	ds_read_b128 v[222:225], v196 offset:21504
	ds_read_b128 v[226:229], v196 offset:22528
	ds_read_b128 v[230:233], v196 offset:23552
	global_load_lds_dwordx4 v[174:175], off
	s_add_i32 m0, s28, 0x2000
	s_add_u32 s28, s80, 0x80000
	v_lshl_add_u64 v[192:193], s[80:81], 0, v[144:145]
	s_addc_u32 s29, s81, 0
	s_add_i32 s31, s31, s16
	global_load_lds_dwordx4 v[192:193], off
	v_lshl_add_u64 v[198:199], s[28:29], 0, v[148:149]
	s_mov_b32 m0, s31
	v_lshl_add_u64 v[234:235], s[4:5], 0, v[146:147]
	global_load_lds_dwordx4 v[198:199], off
	v_lshl_add_u64 v[198:199], s[28:29], 0, v[144:145]
	s_add_i32 m0, s31, 0x2000
	s_nop 0
	global_load_lds_dwordx4 v[198:199], off
	v_lshl_add_u64 v[198:199], s[4:5], 0, v[150:151]
	s_mov_b32 m0, s23
	s_nop 0
	global_load_lds_dwordx4 v[198:199], off
	s_mov_b32 m0, s26
	s_nop 0
	global_load_lds_dwordx4 v[234:235], off
	s_cmp_lg_u32 s99, 0
	s_cbranch_scc1 .Lrw_In_1_r
	s_waitcnt vmcnt(8)
	s_branch .Lrw_In_1_d
.Lrw_In_1_r:
	s_waitcnt vmcnt(24)
	s_mov_b32 s99, 0
; #define PG8_STAGE(bufoff, gbase, voff) do { _Pragma("unroll") for (int _i = 0; _i < 2; ++_i) \
;         __builtin_amdgcn_global_load_lds((const unsigned*)((const char*)(gbase) + (voff)[_i]), (LAS unsigned*)(lds + (bufoff) + ldsw + _i * 8192), 16, 0, 0); } while (0)
; #define PG8_LDA(dst, b, h) do { _Pragma("unroll") for (int m = 0; m < 4; ++m) _Pragma("unroll") for (int k = 0; k < 2; ++k) dst[m][k] = *(const LAS bf16x8*)(lds + PG8_SA(b, h) + aoff + m * 2048 + k * 1024); } while (0)
; #define PG8_LDB(dst, b, h) do { _Pragma("unroll") for (int n = 0; n < 2; ++n) _Pragma("unroll") for (int k = 0; k < 2; ++k) dst[n][k] = *(const LAS bf16x8*)(lds + PG8_SB(b, h) + boff + n * 2048 + k * 1024); } while (0)
; #define PG8_MMA(ai, bj, At, Bt) do { __builtin_amdgcn_s_setprio(1); _Pragma("unroll") for (int m = 0; m < 4; ++m) _Pragma("unroll") for (int n = 0; n < 2; ++n) _Pragma("unroll") for (int k = 0; k < 2; ++k) \
;         acc[ai][bj][m][n] = __builtin_amdgcn_mfma_f32_16x16x32_bf16(Bt[n][k], At[m][k], acc[ai][bj][m][n], 0, 0, 0); __builtin_amdgcn_s_setprio(0); } while (0)
; #define PG8_WAIT_V(n) asm volatile("s_waitcnt vmcnt(" #n ")" ::: "memory")
; #define PG8_WAIT_L(n) asm volatile("s_waitcnt lgkmcnt(" #n ")" ::: "memory")
; #define PG8_BAR __builtin_amdgcn_s_barrier()
; #define PG8_SCHED __builtin_amdgcn_sched_barrier(0)
; template <class Epi>
; __device__ __forceinline__ void gemm_phase(LAS unsigned char* lds, const GemmD g, const Epi& E, int G, int c) {
;     ...
;             PG8_WAIT_V(8); PG8_WAIT_L(0); PG8_BAR; PG8_MMA(1, 0, At, B0); PG8_MMA(1, 1, At, B1); PG8_BAR; PG8_SCHED;
;             PG8_LDB(B0, 1, 0); PG8_LDB(B1, 1, 1); PG8_SCHED; PG8_LDA(At, 1, 0); PG8_STAGE(PG8_SA(0, 1), a2 + hstepA, voffA);
;             PG8_WAIT_V(8); PG8_WAIT_L(0); PG8_BAR; PG8_MMA(0, 0, At, B0); PG8_MMA(0, 1, At, B1); PG8_BAR; PG8_SCHED;
.Lrw_In_1_d:
	s_waitcnt lgkmcnt(0)
	s_barrier
	s_setprio 1
	s_waitcnt lgkmcnt(0)
	v_mfma_f32_16x16x32_bf16 v[60:63], v[128:131], v[184:187], v[60:63]
	v_mfma_f32_16x16x32_bf16 v[56:59], v[136:139], v[184:187], v[56:59]
	v_mfma_f32_16x16x32_bf16 v[44:47], v[128:131], v[210:213], v[44:47]
	v_mfma_f32_16x16x32_bf16 v[40:43], v[136:139], v[210:213], v[40:43]
	v_mfma_f32_16x16x32_bf16 v[28:31], v[128:131], v[218:221], v[28:31]
	v_mfma_f32_16x16x32_bf16 v[24:27], v[136:139], v[218:221], v[24:27]
	v_mfma_f32_16x16x32_bf16 v[12:15], v[128:131], v[226:229], v[12:15]
	v_mfma_f32_16x16x32_bf16 v[8:11], v[136:139], v[226:229], v[8:11]
	v_mfma_f32_16x16x32_bf16 v[60:63], v[132:135], v[188:191], v[60:63]
	v_mfma_f32_16x16x32_bf16 v[56:59], v[140:143], v[188:191], v[56:59]
	v_mfma_f32_16x16x32_bf16 v[44:47], v[132:135], v[214:217], v[44:47]
	v_mfma_f32_16x16x32_bf16 v[40:43], v[140:143], v[214:217], v[40:43]
	v_mfma_f32_16x16x32_bf16 v[28:31], v[132:135], v[222:225], v[28:31]
	v_mfma_f32_16x16x32_bf16 v[24:27], v[140:143], v[222:225], v[24:27]
	v_mfma_f32_16x16x32_bf16 v[12:15], v[132:135], v[230:233], v[12:15]
	v_mfma_f32_16x16x32_bf16 v[8:11], v[140:143], v[230:233], v[8:11]
	s_setprio 0
	s_setprio 1
	v_mfma_f32_16x16x32_bf16 v[52:55], v[162:165], v[184:187], v[52:55]
	v_mfma_f32_16x16x32_bf16 v[48:51], v[170:173], v[184:187], v[48:51]
	v_mfma_f32_16x16x32_bf16 v[36:39], v[162:165], v[210:213], v[36:39]
	v_mfma_f32_16x16x32_bf16 v[32:35], v[170:173], v[210:213], v[32:35]
	v_mfma_f32_16x16x32_bf16 v[20:23], v[162:165], v[218:221], v[20:23]
	v_mfma_f32_16x16x32_bf16 v[16:19], v[170:173], v[218:221], v[16:19]
	v_mfma_f32_16x16x32_bf16 v[4:7], v[162:165], v[226:229], v[4:7]
	v_mfma_f32_16x16x32_bf16 v[0:3], v[170:173], v[226:229], v[0:3]
	v_mfma_f32_16x16x32_bf16 v[52:55], v[166:169], v[188:191], v[52:55]
	v_mfma_f32_16x16x32_bf16 v[48:51], v[180:183], v[188:191], v[48:51]
	v_mfma_f32_16x16x32_bf16 v[36:39], v[166:169], v[214:217], v[36:39]
	v_mfma_f32_16x16x32_bf16 v[32:35], v[180:183], v[214:217], v[32:35]
	v_mfma_f32_16x16x32_bf16 v[20:23], v[166:169], v[222:225], v[20:23]
	v_mfma_f32_16x16x32_bf16 v[16:19], v[180:183], v[222:225], v[16:19]
	v_mfma_f32_16x16x32_bf16 v[4:7], v[166:169], v[230:233], v[4:7]
	v_mfma_f32_16x16x32_bf16 v[0:3], v[180:183], v[230:233], v[0:3]
	s_setprio 0
	s_barrier
	s_add_i32 s28, 0, 0x18000
	s_add_i32 s29, 0, 0x1c000
	v_add_u32_e32 v140, s28, v194
	v_add_u32_e32 v178, s29, v194
	ds_read_b128 v[128:131], v140
	ds_read_b128 v[132:135], v140 offset:1024
	ds_read_b128 v[136:139], v140 offset:2048
	ds_read_b128 v[140:143], v140 offset:3072
	ds_read_b128 v[162:165], v178
	ds_read_b128 v[166:169], v178 offset:1024
	ds_read_b128 v[170:173], v178 offset:2048
	ds_read_b128 v[180:183], v178 offset:3072
	s_add_u32 s4, s4, 0x80000
	s_addc_u32 s5, s5, 0
	s_mov_b32 m0, s30
	v_lshl_add_u64 v[236:237], s[4:5], 0, v[150:151]
	ds_read_b128 v[184:187], v196 offset:32768
	ds_read_b128 v[188:191], v196 offset:33792
	ds_read_b128 v[210:213], v196 offset:34816
	ds_read_b128 v[214:217], v196 offset:35840
	ds_read_b128 v[218:221], v196 offset:36864
	ds_read_b128 v[222:225], v196 offset:37888
	ds_read_b128 v[226:229], v196 offset:38912
	ds_read_b128 v[230:233], v196 offset:39936
	global_load_lds_dwordx4 v[236:237], off
	v_lshl_add_u64 v[236:237], s[4:5], 0, v[146:147]
	s_mov_b32 m0, s35
	s_nop 0
	global_load_lds_dwordx4 v[236:237], off
	s_waitcnt vmcnt(8)
	s_waitcnt lgkmcnt(0)
	s_barrier
	s_setprio 1
	s_waitcnt lgkmcnt(0)
	v_mfma_f32_16x16x32_bf16 v[124:127], v[128:131], v[184:187], v[124:127]
	v_mfma_f32_16x16x32_bf16 v[120:123], v[136:139], v[184:187], v[120:123]
	v_mfma_f32_16x16x32_bf16 v[108:111], v[128:131], v[210:213], v[108:111]
	v_mfma_f32_16x16x32_bf16 v[104:107], v[136:139], v[210:213], v[104:107]
	v_mfma_f32_16x16x32_bf16 v[92:95], v[128:131], v[218:221], v[92:95]
	v_mfma_f32_16x16x32_bf16 v[88:91], v[136:139], v[218:221], v[88:91]
	v_mfma_f32_16x16x32_bf16 v[76:79], v[128:131], v[226:229], v[76:79]
	v_mfma_f32_16x16x32_bf16 v[72:75], v[136:139], v[226:229], v[72:75]
	v_mfma_f32_16x16x32_bf16 v[124:127], v[132:135], v[188:191], v[124:127]
	v_mfma_f32_16x16x32_bf16 v[120:123], v[140:143], v[188:191], v[120:123]
	v_mfma_f32_16x16x32_bf16 v[108:111], v[132:135], v[214:217], v[108:111]
	v_mfma_f32_16x16x32_bf16 v[104:107], v[140:143], v[214:217], v[104:107]
	v_mfma_f32_16x16x32_bf16 v[92:95], v[132:135], v[222:225], v[92:95]
	v_mfma_f32_16x16x32_bf16 v[88:91], v[140:143], v[222:225], v[88:91]
	v_mfma_f32_16x16x32_bf16 v[76:79], v[132:135], v[230:233], v[76:79]
	v_mfma_f32_16x16x32_bf16 v[72:75], v[140:143], v[230:233], v[72:75]
	s_setprio 0
	s_setprio 1
	v_mfma_f32_16x16x32_bf16 v[116:119], v[162:165], v[184:187], v[116:119]
	v_mfma_f32_16x16x32_bf16 v[112:115], v[170:173], v[184:187], v[112:115]
	v_mfma_f32_16x16x32_bf16 v[100:103], v[162:165], v[210:213], v[100:103]
	v_mfma_f32_16x16x32_bf16 v[96:99], v[170:173], v[210:213], v[96:99]
	v_mfma_f32_16x16x32_bf16 v[84:87], v[162:165], v[218:221], v[84:87]
	v_mfma_f32_16x16x32_bf16 v[80:83], v[170:173], v[218:221], v[80:83]
	v_mfma_f32_16x16x32_bf16 v[68:71], v[162:165], v[226:229], v[68:71]
	v_mfma_f32_16x16x32_bf16 v[64:67], v[170:173], v[226:229], v[64:67]
	v_mfma_f32_16x16x32_bf16 v[116:119], v[166:169], v[188:191], v[116:119]
	v_mfma_f32_16x16x32_bf16 v[112:115], v[180:183], v[188:191], v[112:115]
	v_mfma_f32_16x16x32_bf16 v[100:103], v[166:169], v[214:217], v[100:103]
	v_mfma_f32_16x16x32_bf16 v[96:99], v[180:183], v[214:217], v[96:99]
	v_mfma_f32_16x16x32_bf16 v[84:87], v[166:169], v[222:225], v[84:87]
	v_mfma_f32_16x16x32_bf16 v[80:83], v[180:183], v[222:225], v[80:83]
	v_mfma_f32_16x16x32_bf16 v[68:71], v[166:169], v[230:233], v[68:71]
	v_mfma_f32_16x16x32_bf16 v[64:67], v[180:183], v[230:233], v[64:67]
	s_setprio 0
	s_barrier
; #define PG8_STAGE(bufoff, gbase, voff) do { _Pragma("unroll") for (int _i = 0; _i < 2; ++_i) \
;         __builtin_amdgcn_global_load_lds((const unsigned*)((const char*)(gbase) + (voff)[_i]), (LAS unsigned*)(lds + (bufoff) + ldsw + _i * 8192), 16, 0, 0); } while (0)
; #define PG8_LDA(dst, b, h) do { _Pragma("unroll") for (int m = 0; m < 4; ++m) _Pragma("unroll") for (int k = 0; k < 2; ++k) dst[m][k] = *(const LAS bf16x8*)(lds + PG8_SA(b, h) + aoff + m * 2048 + k * 1024); } while (0)
; #define PG8_MMA(ai, bj, At, Bt) do { __builtin_amdgcn_s_setprio(1); _Pragma("unroll") for (int m = 0; m < 4; ++m) _Pragma("unroll") for (int n = 0; n < 2; ++n) _Pragma("unroll") for (int k = 0; k < 2; ++k) \
;         acc[ai][bj][m][n] = __builtin_amdgcn_mfma_f32_16x16x32_bf16(Bt[n][k], At[m][k], acc[ai][bj][m][n], 0, 0, 0); __builtin_amdgcn_s_setprio(0); } while (0)
; #define PG8_WAIT_V(n) asm volatile("s_waitcnt vmcnt(" #n ")" ::: "memory")
; #define PG8_WAIT_L(n) asm volatile("s_waitcnt lgkmcnt(" #n ")" ::: "memory")
; #define PG8_BAR __builtin_amdgcn_s_barrier()
; #define PG8_SCHED __builtin_amdgcn_sched_barrier(0)
; template <class Epi>
; __device__ __forceinline__ void gemm_phase(LAS unsigned char* lds, const GemmD g, const Epi& E, int G, int c) {
;     ...
;             PG8_LDA(At, 1, 1); PG8_STAGE(PG8_SB(1, 0), b3, voffB); PG8_STAGE(PG8_SB(1, 1), b3 + hstepB, voffB); PG8_STAGE(PG8_SA(1, 0), a3, voffA);
;             PG8_WAIT_V(8); PG8_WAIT_L(0); PG8_BAR; PG8_MMA(1, 0, At, B0); PG8_MMA(1, 1, At, B1); PG8_BAR; PG8_SCHED;
;         }
;         if (wr == 0) PG8_BAR;
;     __device__ __forceinline__ void operator()(AccRef acc, int pm, int pn, int z, int wr, int wc, int fr, int fq) const {
;         const int row0 = pm * BM + wr * 64 + fr, cw = wc * 32 + 8 * fq;
;         float rrow[2][4];
; #pragma unroll
;         for (int ai = 0; ai < 2; ++ai)
; #pragma unroll
;             for (int m = 0; m < 4; ++m) rrow[ai][m] = rsq[row0 + ai * HALF + m * 16];
; #pragma unroll
;         for (int ai = 0; ai < 2; ++ai)
; #pragma unroll
;             for (int m = 0; m < 4; ++m) rrow[ai][m] = 1.0f / sqrtf(rrow[ai][m] * (1.0f / DM) + EPS);
	s_add_i32 s4, s28, s16
	v_lshl_add_u64 v[174:175], v[174:175], 0, s[48:49]
	s_mov_b32 m0, s4
	ds_read_b128 v[184:187], v196 offset:49152
	ds_read_b128 v[188:191], v196 offset:50176
	ds_read_b128 v[210:213], v196 offset:51200
	ds_read_b128 v[214:217], v196 offset:52224
	ds_read_b128 v[218:221], v196 offset:53248
	ds_read_b128 v[222:225], v196 offset:54272
	ds_read_b128 v[226:229], v196 offset:55296
	ds_read_b128 v[230:233], v196 offset:56320
	global_load_lds_dwordx4 v[174:175], off
	s_add_i32 m0, s4, 0x2000
	s_add_u32 s4, s80, 0x80080
	v_lshl_add_u64 v[174:175], v[192:193], 0, s[48:49]
	s_addc_u32 s5, s81, 0
	s_add_i32 s28, s29, s16
	global_load_lds_dwordx4 v[174:175], off
	v_lshl_add_u64 v[174:175], s[4:5], 0, v[148:149]
	s_mov_b32 m0, s28
	s_nop 0
	global_load_lds_dwordx4 v[174:175], off
	v_lshl_add_u64 v[174:175], s[4:5], 0, v[144:145]
	s_add_i32 m0, s28, 0x2000
	s_nop 0
	global_load_lds_dwordx4 v[174:175], off
	v_lshl_add_u64 v[174:175], v[198:199], 0, s[48:49]
	s_mov_b32 m0, s36
	s_nop 0
	global_load_lds_dwordx4 v[174:175], off
	v_lshl_add_u64 v[174:175], v[234:235], 0, s[48:49]
	s_mov_b32 m0, s82
	s_nop 0
	global_load_lds_dwordx4 v[174:175], off
	s_waitcnt vmcnt(8)
	s_waitcnt lgkmcnt(0)
	s_barrier
	s_setprio 1
	s_waitcnt lgkmcnt(0)
	v_mfma_f32_16x16x32_bf16 v[60:63], v[128:131], v[184:187], v[60:63]
	v_mfma_f32_16x16x32_bf16 v[56:59], v[136:139], v[184:187], v[56:59]
	v_mfma_f32_16x16x32_bf16 v[44:47], v[128:131], v[210:213], v[44:47]
	v_mfma_f32_16x16x32_bf16 v[40:43], v[136:139], v[210:213], v[40:43]
	v_mfma_f32_16x16x32_bf16 v[28:31], v[128:131], v[218:221], v[28:31]
	v_mfma_f32_16x16x32_bf16 v[24:27], v[136:139], v[218:221], v[24:27]
	v_mfma_f32_16x16x32_bf16 v[12:15], v[128:131], v[226:229], v[12:15]
	v_mfma_f32_16x16x32_bf16 v[8:11], v[136:139], v[226:229], v[8:11]
	v_mfma_f32_16x16x32_bf16 v[60:63], v[132:135], v[188:191], v[60:63]
	v_mfma_f32_16x16x32_bf16 v[56:59], v[140:143], v[188:191], v[56:59]
	v_mfma_f32_16x16x32_bf16 v[44:47], v[132:135], v[214:217], v[44:47]
	v_mfma_f32_16x16x32_bf16 v[40:43], v[140:143], v[214:217], v[40:43]
	v_mfma_f32_16x16x32_bf16 v[28:31], v[132:135], v[222:225], v[28:31]
	v_mfma_f32_16x16x32_bf16 v[24:27], v[140:143], v[222:225], v[24:27]
	v_mfma_f32_16x16x32_bf16 v[12:15], v[132:135], v[230:233], v[12:15]
	v_mfma_f32_16x16x32_bf16 v[8:11], v[140:143], v[230:233], v[8:11]
	s_setprio 0
	s_setprio 1
	v_mfma_f32_16x16x32_bf16 v[52:55], v[162:165], v[184:187], v[52:55]
	v_mfma_f32_16x16x32_bf16 v[48:51], v[170:173], v[184:187], v[48:51]
	v_mfma_f32_16x16x32_bf16 v[36:39], v[162:165], v[210:213], v[36:39]
	v_mfma_f32_16x16x32_bf16 v[32:35], v[170:173], v[210:213], v[32:35]
	v_mfma_f32_16x16x32_bf16 v[20:23], v[162:165], v[218:221], v[20:23]
	v_mfma_f32_16x16x32_bf16 v[16:19], v[170:173], v[218:221], v[16:19]
	v_mfma_f32_16x16x32_bf16 v[4:7], v[162:165], v[226:229], v[4:7]
	v_mfma_f32_16x16x32_bf16 v[0:3], v[170:173], v[226:229], v[0:3]
	v_mfma_f32_16x16x32_bf16 v[52:55], v[166:169], v[188:191], v[52:55]
	v_mfma_f32_16x16x32_bf16 v[48:51], v[180:183], v[188:191], v[48:51]
	v_mfma_f32_16x16x32_bf16 v[36:39], v[166:169], v[214:217], v[36:39]
	v_mfma_f32_16x16x32_bf16 v[32:35], v[180:183], v[214:217], v[32:35]
	v_mfma_f32_16x16x32_bf16 v[20:23], v[166:169], v[222:225], v[20:23]
	v_mfma_f32_16x16x32_bf16 v[16:19], v[180:183], v[222:225], v[16:19]
	v_mfma_f32_16x16x32_bf16 v[4:7], v[166:169], v[230:233], v[4:7]
	v_mfma_f32_16x16x32_bf16 v[0:3], v[180:183], v[230:233], v[0:3]
	s_setprio 0
	s_barrier
	s_add_i32 s27, s27, 2
	s_add_u32 s42, s42, 0x100
	s_addc_u32 s43, s43, 0
	s_add_u32 s19, s19, 0x100
	s_addc_u32 s22, s22, 0
	s_cmp_gt_u32 s27, 29
	s_cbranch_scc0 .LBB0_394
	s_and_b64 vcc, exec, s[46:47]
	s_cbranch_vccz .LBB0_397
	s_barrier
.LBB0_397:
	v_lshl_add_u32 v186, s2, 8, v153
	v_ashrrev_i32_e32 v187, 31, v186
	v_lshl_add_u64 v[132:133], v[186:187], 2, s[12:13]
	v_mov_b32_e32 v134, v241
	v_or_b32_e32 v182, 16, v186
	v_ashrrev_i32_e32 v183, 31, v182
	v_lshl_add_u64 v[128:129], v[182:183], 2, s[12:13]
	v_mov_b32_e32 v135, v242
	v_or_b32_e32 v172, 32, v186
	v_ashrrev_i32_e32 v173, 31, v172
	v_lshl_add_u64 v[128:129], v[172:173], 2, s[12:13]
	v_mov_b32_e32 v136, v243
	v_or_b32_e32 v166, 48, v186
	v_ashrrev_i32_e32 v167, 31, v166
	v_lshl_add_u64 v[128:129], v[166:167], 2, s[12:13]
	v_mov_b32_e32 v137, v244
	v_mov_b32_e32 v131, v245
	v_mov_b32_e32 v130, v246
	s_nop 0
	v_mov_b32_e32 v129, v247
	v_mov_b32_e32 v128, v248
	v_add_u32_e32 v162, 0x80, v186
	v_ashrrev_i32_e32 v163, 31, v162
	s_cmp_gt_i32 s9, 7
	v_fmamk_f32 v132, v134, 0x3a000000, v201
	v_cmp_gt_f32_e32 vcc, s51, v132
	v_mul_f32_e32 v133, 0x4f800000, v132
	v_fmamk_f32 v131, v131, 0x3a000000, v201
	v_cndmask_b32_e32 v132, v132, v133, vcc
	v_sqrt_f32_e32 v133, v132
	v_fmamk_f32 v130, v130, 0x3a000000, v201
	v_fmamk_f32 v129, v129, 0x3a000000, v201
	v_fmamk_f32 v128, v128, 0x3a000000, v201
	v_add_u32_e32 v134, -1, v133
	v_fma_f32 v138, -v134, v133, v132
	v_cmp_ge_f32_e64 s[42:43], 0, v138
	v_add_u32_e32 v138, 1, v133
	s_nop 0
	v_cndmask_b32_e64 v134, v133, v134, s[42:43]
	v_fma_f32 v133, -v138, v133, v132
	v_cmp_lt_f32_e64 s[42:43], 0, v133
	s_nop 1
	v_cndmask_b32_e64 v133, v134, v138, s[42:43]
	v_mul_f32_e32 v134, 0x37800000, v133
	v_cndmask_b32_e32 v133, v133, v134, vcc
	v_cmp_class_f32_e32 vcc, v132, v202
	s_nop 1
	v_cndmask_b32_e32 v132, v133, v132, vcc
	v_div_scale_f32 v133, s[4:5], v132, v132, 1.0
	v_rcp_f32_e32 v134, v133
	s_nop 0
	v_fma_f32 v138, -v133, v134, 1.0
	v_fmac_f32_e32 v134, v138, v134
	v_div_scale_f32 v138, vcc, 1.0, v132, 1.0
	v_mul_f32_e32 v139, v138, v134
	v_fma_f32 v140, -v133, v139, v138
	v_fmac_f32_e32 v139, v140, v134
;     __device__ __forceinline__ void operator()(AccRef acc, int pm, int pn, int z, int wr, int wc, int fr, int fq) const {
;     ...
;         for (int ai = 0; ai < 2; ++ai)
; #pragma unroll
;             for (int m = 0; m < 4; ++m) rrow[ai][m] = 1.0f / sqrtf(rrow[ai][m] * (1.0f / DM) + EPS);
	v_fma_f32 v133, -v133, v139, v138
	v_div_fmas_f32 v133, v133, v134, v139
	v_div_fixup_f32 v190, v133, v132, 1.0
	v_fmamk_f32 v132, v135, 0x3a000000, v201
	v_cmp_gt_f32_e32 vcc, s51, v132
	v_mul_f32_e32 v133, 0x4f800000, v132
	s_nop 0
	v_cndmask_b32_e32 v132, v132, v133, vcc
	v_sqrt_f32_e32 v133, v132
	s_nop 0
	v_add_u32_e32 v134, -1, v133
	v_fma_f32 v135, -v134, v133, v132
	v_cmp_ge_f32_e64 s[42:43], 0, v135
	v_add_u32_e32 v135, 1, v133
	s_nop 0
	v_cndmask_b32_e64 v134, v133, v134, s[42:43]
	v_fma_f32 v133, -v135, v133, v132
	v_cmp_lt_f32_e64 s[42:43], 0, v133
	s_nop 1
	v_cndmask_b32_e64 v133, v134, v135, s[42:43]
	v_mul_f32_e32 v134, 0x37800000, v133
	v_cndmask_b32_e32 v133, v133, v134, vcc
	v_cmp_class_f32_e32 vcc, v132, v202
	s_nop 1
	v_cndmask_b32_e32 v132, v133, v132, vcc
	v_div_scale_f32 v133, s[4:5], v132, v132, 1.0
	v_rcp_f32_e32 v134, v133
	s_nop 0
	v_fma_f32 v135, -v133, v134, 1.0
	v_fmac_f32_e32 v134, v135, v134
	v_div_scale_f32 v135, vcc, 1.0, v132, 1.0
	v_mul_f32_e32 v138, v135, v134
	v_fma_f32 v139, -v133, v138, v135
	v_fmac_f32_e32 v138, v139, v134
	v_fma_f32 v133, -v133, v138, v135
	v_div_fmas_f32 v133, v133, v134, v138
	v_div_fixup_f32 v188, v133, v132, 1.0
	v_fmamk_f32 v132, v136, 0x3a000000, v201
	v_cmp_gt_f32_e32 vcc, s51, v132
	v_mul_f32_e32 v133, 0x4f800000, v132
	s_nop 0
	v_cndmask_b32_e32 v132, v132, v133, vcc
	v_sqrt_f32_e32 v133, v132
	s_nop 0
	v_add_u32_e32 v134, -1, v133
	v_fma_f32 v135, -v134, v133, v132
	v_cmp_ge_f32_e64 s[42:43], 0, v135
	v_add_u32_e32 v135, 1, v133
	s_nop 0
	v_cndmask_b32_e64 v134, v133, v134, s[42:43]
	v_fma_f32 v133, -v135, v133, v132
	v_cmp_lt_f32_e64 s[42:43], 0, v133
	s_nop 1
	v_cndmask_b32_e64 v133, v134, v135, s[42:43]
	v_mul_f32_e32 v134, 0x37800000, v133
	v_cndmask_b32_e32 v133, v133, v134, vcc
	v_cmp_class_f32_e32 vcc, v132, v202
	s_nop 1
	v_cndmask_b32_e32 v132, v133, v132, vcc
	v_div_scale_f32 v133, s[4:5], v132, v132, 1.0
	v_rcp_f32_e32 v134, v133
	s_nop 0
	v_fma_f32 v135, -v133, v134, 1.0
	v_fmac_f32_e32 v134, v135, v134
	v_div_scale_f32 v135, vcc, 1.0, v132, 1.0
	v_mul_f32_e32 v136, v135, v134
	v_fma_f32 v138, -v133, v136, v135
	v_fmac_f32_e32 v136, v138, v134
	v_fma_f32 v133, -v133, v136, v135
	v_div_fmas_f32 v133, v133, v134, v136
	v_div_fixup_f32 v180, v133, v132, 1.0
	v_fmamk_f32 v132, v137, 0x3a000000, v201
	v_cmp_gt_f32_e32 vcc, s51, v132
	v_mul_f32_e32 v133, 0x4f800000, v132
	s_nop 0
	v_cndmask_b32_e32 v132, v132, v133, vcc
	v_sqrt_f32_e32 v133, v132
	s_nop 0
	v_add_u32_e32 v134, -1, v133
	v_fma_f32 v135, -v134, v133, v132
	v_cmp_ge_f32_e64 s[42:43], 0, v135
	v_add_u32_e32 v135, 1, v133
	s_nop 0
	v_cndmask_b32_e64 v134, v133, v134, s[42:43]
	v_fma_f32 v133, -v135, v133, v132
	v_cmp_lt_f32_e64 s[42:43], 0, v133
	s_nop 1
	v_cndmask_b32_e64 v133, v134, v135, s[42:43]
	v_mul_f32_e32 v134, 0x37800000, v133
	v_cndmask_b32_e32 v133, v133, v134, vcc
	v_cmp_class_f32_e32 vcc, v132, v202
	s_nop 1
	v_cndmask_b32_e32 v132, v133, v132, vcc
	v_div_scale_f32 v133, s[4:5], v132, v132, 1.0
	v_rcp_f32_e32 v134, v133
	s_nop 0
	v_fma_f32 v135, -v133, v134, 1.0
	v_fmac_f32_e32 v134, v135, v134
	v_div_scale_f32 v135, vcc, 1.0, v132, 1.0
	v_mul_f32_e32 v136, v135, v134
	v_fma_f32 v137, -v133, v136, v135
	v_fmac_f32_e32 v136, v137, v134
	v_fma_f32 v133, -v133, v136, v135
	v_div_fmas_f32 v133, v133, v134, v136
	v_div_fixup_f32 v184, v133, v132, 1.0
	v_cmp_gt_f32_e32 vcc, s51, v131
	v_mul_f32_e32 v132, 0x4f800000, v131
	s_nop 0
	v_cndmask_b32_e32 v131, v131, v132, vcc
	v_sqrt_f32_e32 v132, v131
	s_nop 0
	v_add_u32_e32 v133, -1, v132
	v_fma_f32 v134, -v133, v132, v131
	v_cmp_ge_f32_e64 s[42:43], 0, v134
	v_add_u32_e32 v134, 1, v132
	s_nop 0
	v_cndmask_b32_e64 v133, v132, v133, s[42:43]
	v_fma_f32 v132, -v134, v132, v131
	v_cmp_lt_f32_e64 s[42:43], 0, v132
	s_nop 1
	v_cndmask_b32_e64 v132, v133, v134, s[42:43]
;     __device__ __forceinline__ void operator()(AccRef acc, int pm, int pn, int z, int wr, int wc, int fr, int fq) const {
;     ...
;         for (int ai = 0; ai < 2; ++ai)
; #pragma unroll
;             for (int m = 0; m < 4; ++m) rrow[ai][m] = 1.0f / sqrtf(rrow[ai][m] * (1.0f / DM) + EPS);
;         if (pn < 8) {
	v_mul_f32_e32 v133, 0x37800000, v132
	v_cndmask_b32_e32 v132, v132, v133, vcc
	v_cmp_class_f32_e32 vcc, v131, v202
	s_nop 1
	v_cndmask_b32_e32 v131, v132, v131, vcc
	v_div_scale_f32 v132, s[4:5], v131, v131, 1.0
	v_rcp_f32_e32 v133, v132
	s_nop 0
	v_fma_f32 v134, -v132, v133, 1.0
	v_fmac_f32_e32 v133, v134, v133
	v_div_scale_f32 v134, vcc, 1.0, v131, 1.0
	v_mul_f32_e32 v135, v134, v133
	v_fma_f32 v136, -v132, v135, v134
	v_fmac_f32_e32 v135, v136, v133
	v_fma_f32 v132, -v132, v135, v134
	v_div_fmas_f32 v132, v132, v133, v135
	v_div_fixup_f32 v174, v132, v131, 1.0
	v_cmp_gt_f32_e32 vcc, s51, v130
	v_mul_f32_e32 v131, 0x4f800000, v130
	s_nop 0
	v_cndmask_b32_e32 v130, v130, v131, vcc
	v_sqrt_f32_e32 v131, v130
	s_nop 0
	v_add_u32_e32 v132, -1, v131
	v_fma_f32 v133, -v132, v131, v130
	v_cmp_ge_f32_e64 s[42:43], 0, v133
	v_add_u32_e32 v133, 1, v131
	s_nop 0
	v_cndmask_b32_e64 v132, v131, v132, s[42:43]
	v_fma_f32 v131, -v133, v131, v130
	v_cmp_lt_f32_e64 s[42:43], 0, v131
	s_nop 1
	v_cndmask_b32_e64 v131, v132, v133, s[42:43]
	v_mul_f32_e32 v132, 0x37800000, v131
	v_cndmask_b32_e32 v131, v131, v132, vcc
	v_cmp_class_f32_e32 vcc, v130, v202
	s_nop 1
	v_cndmask_b32_e32 v130, v131, v130, vcc
	v_div_scale_f32 v131, s[4:5], v130, v130, 1.0
	v_rcp_f32_e32 v132, v131
	s_nop 0
	v_fma_f32 v133, -v131, v132, 1.0
	v_fmac_f32_e32 v132, v133, v132
	v_div_scale_f32 v133, vcc, 1.0, v130, 1.0
	v_mul_f32_e32 v134, v133, v132
	v_fma_f32 v135, -v131, v134, v133
	v_fmac_f32_e32 v134, v135, v132
	v_fma_f32 v131, -v131, v134, v133
	v_div_fmas_f32 v131, v131, v132, v134
	v_div_fixup_f32 v170, v131, v130, 1.0
	v_cmp_gt_f32_e32 vcc, s51, v129
	v_mul_f32_e32 v130, 0x4f800000, v129
	s_nop 0
	v_cndmask_b32_e32 v129, v129, v130, vcc
	v_sqrt_f32_e32 v130, v129
	s_nop 0
	v_add_u32_e32 v131, -1, v130
	v_fma_f32 v132, -v131, v130, v129
	v_cmp_ge_f32_e64 s[42:43], 0, v132
	v_add_u32_e32 v132, 1, v130
	s_nop 0
	v_cndmask_b32_e64 v131, v130, v131, s[42:43]
	v_fma_f32 v130, -v132, v130, v129
	v_cmp_lt_f32_e64 s[42:43], 0, v130
	s_nop 1
	v_cndmask_b32_e64 v130, v131, v132, s[42:43]
	v_mul_f32_e32 v131, 0x37800000, v130
	v_cndmask_b32_e32 v130, v130, v131, vcc
	v_cmp_class_f32_e32 vcc, v129, v202
	s_nop 1
	v_cndmask_b32_e32 v129, v130, v129, vcc
	v_div_scale_f32 v130, s[4:5], v129, v129, 1.0
	v_rcp_f32_e32 v131, v130
	s_nop 0
	v_fma_f32 v132, -v130, v131, 1.0
	v_fmac_f32_e32 v131, v132, v131
	v_div_scale_f32 v132, vcc, 1.0, v129, 1.0
	v_mul_f32_e32 v133, v132, v131
	v_fma_f32 v134, -v130, v133, v132
	v_fmac_f32_e32 v133, v134, v131
	v_fma_f32 v130, -v130, v133, v132
	v_div_fmas_f32 v130, v130, v131, v133
	v_div_fixup_f32 v168, v130, v129, 1.0
	v_cmp_gt_f32_e32 vcc, s51, v128
	v_mul_f32_e32 v129, 0x4f800000, v128
	s_nop 0
	v_cndmask_b32_e32 v128, v128, v129, vcc
	v_sqrt_f32_e32 v129, v128
	s_nop 0
	v_add_u32_e32 v130, -1, v129
	v_fma_f32 v131, -v130, v129, v128
	v_cmp_ge_f32_e64 s[42:43], 0, v131
	v_add_u32_e32 v131, 1, v129
	s_nop 0
	v_cndmask_b32_e64 v130, v129, v130, s[42:43]
	v_fma_f32 v129, -v131, v129, v128
	v_cmp_lt_f32_e64 s[42:43], 0, v129
	s_nop 1
	v_cndmask_b32_e64 v129, v130, v131, s[42:43]
	v_mul_f32_e32 v130, 0x37800000, v129
	v_cndmask_b32_e32 v129, v129, v130, vcc
	v_cmp_class_f32_e32 vcc, v128, v202
	s_nop 1
	v_cndmask_b32_e32 v128, v129, v128, vcc
	v_div_scale_f32 v129, s[4:5], v128, v128, 1.0
	v_rcp_f32_e32 v130, v129
	s_mov_b64 s[4:5], -1
	v_fma_f32 v131, -v129, v130, 1.0
	v_fmac_f32_e32 v130, v131, v130
	v_div_scale_f32 v131, vcc, 1.0, v128, 1.0
	v_mul_f32_e32 v132, v131, v130
	v_fma_f32 v133, -v129, v132, v131
	v_fmac_f32_e32 v132, v133, v130
	v_fma_f32 v129, -v129, v132, v131
	v_div_fmas_f32 v129, v129, v130, v132
	v_div_fixup_f32 v164, v129, v128, 1.0
	s_cbranch_scc1 .LBB0_400
	s_andn2_b64 vcc, exec, s[4:5]
	s_cbranch_vccz .LBB0_469
